# P4 sliding-window output: half-wave 8-byte row pieces paired with v_permlane32_swap, 16-byte stores (4 per task, was 8)
# baseline (speedup 1.0000x reference)
; __device__ __forceinline__ int crow(int r, int hi) { return (r & 3) + 8 * (r >> 2) + 4 * hi; }
; #define MFMA32(a, b, c) __builtin_amdgcn_mfma_f32_32x32x16_bf16((a), (b), (c), 0, 0, 0)
; __device__ __forceinline__ void swa_item(int it, LAS unsigned char* lds, const bf16_t* SQ, const bf16_t* SK, const bf16_t* SV, const float* sinks, bf16_t* MIX, int tid, int wid, int lane) {
;     ...
;         const int hl = tk >> 2, qt = tk & 3, head = kvh * 8 + hh * 4 + hl;
;         const long qrow = rb + pos0 + 32 * qt + x;
;         bf16x8 qf[4];
; #pragma unroll
;         for (int ks = 0; ks < 4; ++ks) qf[ks] = *(const bf16x8*)(SQ + qrow * 1024 + head * 64 + 16 * ks + 8 * hi);
;         f32x16 st[5];
; #pragma unroll
;         for (int t = 0; t < 5; ++t) {
;             int kp = pos0 + 32 * qt - 128 + 32 * t + x; if (kp < 0) kp = 0;
;             const bf16_t* kptr = SK + (rb + kp) * 128 + kvh * 64 + 8 * hi;
;             f32x16 acc = {};
; #pragma unroll
;             for (int ks = 0; ks < 4; ++ks) acc = MFMA32(*(const bf16x8*)(kptr + 16 * ks), qf[ks], acc);
;             st[t] = acc;
;         }
;         const float sink2 = sinks[head] * LOG2E;
;         float mx = sink2;
; #pragma unroll
;         for (int r = 0; r < 16; ++r) { const int kk = crow(r, hi); if (kk <= x || (n == 0)) st[0][r] = -1e30f; if (kk > x) st[4][r] = -1e30f; }
; #pragma unroll
;         for (int t = 1; t < 4; ++t) if (n == 0 && qt + t < 4) {
; #pragma unroll
;             for (int r = 0; r < 16; ++r) st[t][r] = -1e30f; }
.LBB0_1033:
	global_load_dwordx4 v[66:69], v[118:119], off offset:-64
	global_load_dwordx4 v[176:179], v[118:119], off offset:-32
	global_load_dwordx4 v[180:183], v[118:119], off
	global_load_dwordx4 v[82:85], v[118:119], off offset:32
	global_load_dwordx4 v[34:37], v[108:109], off
	global_load_dwordx4 v[38:41], v[108:109], off offset:32
	global_load_dwordx4 v[42:45], v[108:109], off offset:64
	global_load_dwordx4 v[46:49], v[108:109], off offset:96
	global_load_dwordx4 v[70:73], v[110:111], off
	global_load_dwordx4 v[74:77], v[110:111], off offset:32
	global_load_dwordx4 v[78:81], v[110:111], off offset:64
	global_load_dwordx4 v[184:187], v[110:111], off offset:96
	global_load_dwordx4 v[208:211], v[112:113], off
	global_load_dwordx4 v[212:215], v[112:113], off offset:32
	global_load_dwordx4 v[216:219], v[112:113], off offset:64
	global_load_dwordx4 v[220:223], v[112:113], off offset:96
	global_load_dwordx4 v[224:227], v[114:115], off
	global_load_dwordx4 v[228:231], v[114:115], off offset:32
	global_load_dwordx4 v[232:235], v[114:115], off offset:64
	global_load_dwordx4 v[236:239], v[114:115], off offset:96
	global_load_dwordx4 v[240:243], v[116:117], off
	global_load_dwordx4 v[244:247], v[116:117], off offset:32
	global_load_dwordx4 v[248:251], v[116:117], off offset:64
	s_mov_b32 s14, 0x3fb8aa3b
	s_waitcnt vmcnt(18)
	v_mfma_f32_32x32x16_bf16 v[2:17], v[34:37], v[66:69], 0
	s_nop 0
	s_nop 0
	s_waitcnt vmcnt(17)
	v_mfma_f32_32x32x16_bf16 v[2:17], v[38:41], v[176:179], v[2:17]
	s_nop 0
	s_waitcnt vmcnt(16)
	v_mfma_f32_32x32x16_bf16 v[2:17], v[42:45], v[180:183], v[2:17]
	s_nop 0
	s_waitcnt vmcnt(15)
	v_mfma_f32_32x32x16_bf16 v[2:17], v[46:49], v[82:85], v[2:17]
	s_nop 0
	s_waitcnt vmcnt(14)
	v_mfma_f32_32x32x16_bf16 v[18:33], v[70:73], v[66:69], 0
	s_waitcnt vmcnt(13)
	v_mfma_f32_32x32x16_bf16 v[18:33], v[74:77], v[176:179], v[18:33]
	s_nop 0
	s_waitcnt vmcnt(12)
	v_mfma_f32_32x32x16_bf16 v[18:33], v[78:81], v[180:183], v[18:33]
	s_nop 0
	s_waitcnt vmcnt(11)
	v_mfma_f32_32x32x16_bf16 v[18:33], v[184:187], v[82:85], v[18:33]
	s_nop 0
	s_nop 10
	v_cndmask_b32_e64 v195, v19, v173, s[96:97]
	v_cndmask_b32_e64 v196, v18, v173, s[96:97]
	v_cndmask_b32_e64 v193, v21, v173, s[96:97]
	v_cndmask_b32_e64 v194, v20, v173, s[96:97]
	v_cndmask_b32_e64 v191, v23, v173, s[96:97]
	v_cndmask_b32_e64 v192, v22, v173, s[96:97]
	v_cndmask_b32_e64 v188, v25, v173, s[96:97]
	v_cndmask_b32_e64 v189, v24, v173, s[96:97]
	s_waitcnt vmcnt(10)
	v_mfma_f32_32x32x16_bf16 v[50:65], v[208:211], v[66:69], 0
	global_load_dwordx4 v[208:211], v[116:117], off offset:96
	s_nop 0
	s_waitcnt vmcnt(10)
	v_mfma_f32_32x32x16_bf16 v[50:65], v[212:215], v[176:179], v[50:65]
	s_nop 0
	s_waitcnt vmcnt(9)
	v_mfma_f32_32x32x16_bf16 v[50:65], v[216:219], v[180:183], v[50:65]
	s_nop 0
	s_waitcnt vmcnt(8)
	v_mfma_f32_32x32x16_bf16 v[50:65], v[220:223], v[82:85], v[50:65]
	s_nop 0
	s_nop 10
	v_cndmask_b32_e64 v200, v58, v173, s[0:1]
	v_cndmask_b32_e64 v58, v53, v173, s[0:1]
	v_cndmask_b32_e64 v53, v51, v173, s[0:1]
	v_cndmask_b32_e64 v203, v50, v173, s[0:1]
	v_cndmask_b32_e64 v52, v52, v173, s[0:1]
	v_cndmask_b32_e64 v55, v55, v173, s[0:1]
	v_cndmask_b32_e64 v201, v57, v173, s[0:1]
	v_cndmask_b32_e64 v202, v56, v173, s[0:1]
	v_cndmask_b32_e64 v59, v59, v173, s[0:1]
	v_cndmask_b32_e64 v199, v61, v173, s[0:1]
	v_cndmask_b32_e64 v61, v60, v173, s[0:1]
	v_cndmask_b32_e64 v197, v63, v173, s[0:1]
	v_cndmask_b32_e64 v198, v62, v173, s[0:1]
	s_waitcnt vmcnt(7)
	v_mfma_f32_32x32x16_bf16 v[34:49], v[224:227], v[66:69], 0
	s_waitcnt vmcnt(6)
	v_mfma_f32_32x32x16_bf16 v[34:49], v[228:231], v[176:179], v[34:49]
	s_nop 0
	s_waitcnt vmcnt(5)
	v_mfma_f32_32x32x16_bf16 v[34:49], v[232:235], v[180:183], v[34:49]
	s_nop 0
	s_waitcnt vmcnt(4)
	v_mfma_f32_32x32x16_bf16 v[34:49], v[236:239], v[82:85], v[34:49]
	s_nop 0
	s_nop 10
	v_cndmask_b32_e64 v204, v35, v173, s[6:7]
	v_cndmask_b32_e64 v205, v34, v173, s[6:7]
	v_cndmask_b32_e64 v63, v36, v173, s[6:7]
	v_cndmask_b32_e64 v25, v43, v173, s[6:7]
	v_cndmask_b32_e64 v23, v45, v173, s[6:7]
	v_cndmask_b32_e64 v24, v44, v173, s[6:7]
	v_cndmask_b32_e64 v21, v47, v173, s[6:7]
	v_cndmask_b32_e64 v22, v46, v173, s[6:7]
	v_cndmask_b32_e64 v19, v49, v173, s[6:7]
	v_cndmask_b32_e64 v20, v48, v173, s[6:7]
	s_waitcnt vmcnt(3)
	v_mfma_f32_32x32x16_bf16 v[66:81], v[240:243], v[66:69], 0
	s_waitcnt vmcnt(2)
	v_mfma_f32_32x32x16_bf16 v[66:81], v[244:247], v[176:179], v[66:81]
	s_nop 0
	v_cndmask_b32_e64 v186, v27, v173, s[96:97]
	v_cndmask_b32_e64 v187, v26, v173, s[96:97]
	v_cndmask_b32_e64 v184, v29, v173, s[96:97]
	v_cndmask_b32_e64 v185, v28, v173, s[96:97]
	v_cndmask_b32_e64 v29, v39, v173, s[6:7]
	v_cndmask_b32_e64 v27, v41, v173, s[6:7]
	v_cndmask_b32_e64 v28, v40, v173, s[6:7]
	v_cndmask_b32_e64 v26, v42, v173, s[6:7]
	s_waitcnt vmcnt(1)
	v_mfma_f32_32x32x16_bf16 v[66:81], v[248:251], v[180:183], v[66:81]
	s_nop 0
	v_cndmask_b32_e64 v180, v6, v173, s[72:73]
	v_cndmask_b32_e64 v182, v31, v173, s[96:97]
	v_cndmask_b32_e64 v183, v30, v173, s[96:97]
	v_cndmask_b32_e64 v181, v32, v173, s[96:97]
	v_cndmask_b32_e64 v31, v65, v173, s[0:1]
	v_cndmask_b32_e64 v65, v54, v173, s[0:1]
	v_cndmask_b32_e64 v32, v37, v173, s[6:7]
	v_cndmask_b32_e64 v30, v38, v173, s[6:7]
	s_waitcnt vmcnt(0)
; __device__ __forceinline__ int crow(int r, int hi) { return (r & 3) + 8 * (r >> 2) + 4 * hi; }
; __device__ __forceinline__ void swa_item(int it, LAS unsigned char* lds, const bf16_t* SQ, const bf16_t* SK, const bf16_t* SV, const float* sinks, bf16_t* MIX, int tid, int wid, int lane) {
;     ...
;         const float sink2 = sinks[head] * LOG2E;
;         float mx = sink2;
; #pragma unroll
;         for (int r = 0; r < 16; ++r) { const int kk = crow(r, hi); if (kk <= x || (n == 0)) st[0][r] = -1e30f; if (kk > x) st[4][r] = -1e30f; }
; #pragma unroll
;         for (int t = 1; t < 4; ++t) if (n == 0 && qt + t < 4) {
; #pragma unroll
;             for (int r = 0; r < 16; ++r) st[t][r] = -1e30f; }
; #pragma unroll
;         for (int t = 0; t < 5; ++t)
; #pragma unroll
;             for (int r = 0; r < 16; ++r) mx = fmaxf(mx, st[t][r]);
;         mx = fmaxf(mx, __shfl_xor(mx, 32));
;         float sum = 0.f;
; #pragma unroll
;         for (int t = 0; t < 5; ++t)
; #pragma unroll
;             for (int r = 0; r < 16; ++r) { const float p = __builtin_amdgcn_exp2f(st[t][r] - mx); st[t][r] = p; sum += p; }
;         sum += __shfl_xor(sum, 32); sum += __builtin_amdgcn_exp2f(sink2 - mx);
	v_mfma_f32_32x32x16_bf16 v[66:81], v[208:211], v[82:85], v[66:81]
	global_load_dword v82, v89, s[10:11]
	v_cndmask_b32_e64 v176, v2, v173, s[64:65]
	v_cndmask_b32_e64 v177, v3, v173, s[66:67]
	v_cndmask_b32_e64 v178, v4, v173, s[68:69]
	v_cndmask_b32_e64 v179, v5, v173, s[70:71]
	s_nop 6
	v_cndmask_b32_e64 v2, v66, v173, s[2:3]
	v_cndmask_b32_e64 v175, v2, v66, s[4:5]
	v_cndmask_b32_e64 v66, v73, v173, s[28:29]
	v_cndmask_b32_e64 v73, v10, v173, s[80:81]
	v_cndmask_b32_e64 v83, v69, v173, s[12:13]
	v_cndmask_b32_e64 v69, v70, v173, s[16:17]
	v_cndmask_b32_e64 v70, v7, v173, s[74:75]
	v_cndmask_b32_e64 v85, v173, v67, s[4:5]
	v_cndmask_b32_e64 v84, v68, v173, s[8:9]
	v_cndmask_b32_e64 v68, v71, v173, s[20:21]
	v_cndmask_b32_e64 v71, v8, v173, s[76:77]
	v_cndmask_b32_e64 v67, v72, v173, s[24:25]
	v_cndmask_b32_e64 v72, v9, v173, s[78:79]
	v_cndmask_b32_e64 v9, v74, v173, s[34:35]
	v_cndmask_b32_e64 v74, v11, v173, s[82:83]
	v_cndmask_b32_e64 v8, v75, v173, s[38:39]
	v_cndmask_b32_e64 v75, v12, v173, s[84:85]
	v_cndmask_b32_e64 v7, v76, v173, s[42:43]
	v_cndmask_b32_e64 v76, v13, v173, s[86:87]
	v_cndmask_b32_e64 v6, v77, v173, s[46:47]
	v_cndmask_b32_e64 v77, v14, v173, s[88:89]
	v_cndmask_b32_e64 v5, v78, v173, s[50:51]
	v_cndmask_b32_e64 v78, v15, v173, s[90:91]
	v_cndmask_b32_e64 v4, v79, v173, s[54:55]
	v_cndmask_b32_e64 v79, v16, v173, s[92:93]
	v_cndmask_b32_e64 v3, v80, v173, s[58:59]
	v_cndmask_b32_e64 v80, v17, v173, s[94:95]
	v_cndmask_b32_e64 v2, v81, v173, s[62:63]
	v_cndmask_b32_e64 v81, v33, v173, s[96:97]
	v_cndmask_b32_e64 v33, v64, v173, s[0:1]
	s_waitcnt vmcnt(0)
	v_mul_f32_e32 v10, 0x3fb8aa3b, v82
	v_max3_f32 v10, v10, v176, v177
	v_max3_f32 v10, v10, v178, v179
	v_max3_f32 v10, v10, v180, v70
	v_max3_f32 v10, v10, v71, v72
	v_max3_f32 v10, v10, v73, v74
	v_max3_f32 v10, v10, v75, v76
	v_max3_f32 v10, v10, v77, v78
	v_max3_f32 v10, v10, v79, v80
	v_max3_f32 v10, v10, v196, v195
	v_max3_f32 v10, v10, v194, v193
	v_max3_f32 v10, v10, v192, v191
	v_max3_f32 v10, v10, v189, v188
	v_max3_f32 v10, v10, v187, v186
	v_max3_f32 v10, v10, v185, v184
	v_max3_f32 v10, v10, v183, v182
	v_max3_f32 v10, v10, v181, v81
	v_max3_f32 v10, v10, v203, v53
	v_max3_f32 v10, v10, v52, v58
	v_max3_f32 v10, v10, v65, v55
	v_max3_f32 v10, v10, v202, v201
	v_max3_f32 v10, v10, v200, v59
	v_max3_f32 v10, v10, v61, v199
	v_max3_f32 v10, v10, v198, v197
	v_max3_f32 v10, v10, v33, v31
	v_max3_f32 v10, v10, v205, v204
	v_max3_f32 v10, v10, v63, v32
	v_max3_f32 v10, v10, v30, v29
	v_max3_f32 v10, v10, v28, v27
	v_max3_f32 v10, v10, v26, v25
	v_max3_f32 v10, v10, v24, v23
	v_max3_f32 v10, v10, v22, v21
	v_max3_f32 v10, v10, v20, v19
	v_max3_f32 v10, v10, v175, v85
	v_max3_f32 v10, v10, v84, v83
	v_max3_f32 v10, v10, v69, v68
	v_max3_f32 v10, v10, v67, v66
	v_max3_f32 v10, v10, v9, v8
	v_max3_f32 v10, v10, v7, v6
	v_max3_f32 v10, v10, v5, v4
	v_max3_f32 v10, v10, v3, v2
	ds_bpermute_b32 v11, v174, v10
	s_waitcnt lgkmcnt(0)
	v_max_f32_e32 v11, v11, v11
	v_max_f32_e32 v11, v10, v11
	v_sub_f32_e32 v10, v176, v11
	v_exp_f32_e32 v10, v10
	v_sub_f32_e32 v12, v177, v11
	v_exp_f32_e32 v12, v12
	v_sub_f32_e32 v37, v75, v11
	v_add_f32_e32 v13, 0, v10
	v_exp_f32_e32 v38, v37
	v_add_f32_e32 v14, v12, v13
	v_sub_f32_e32 v13, v178, v11
	v_exp_f32_e32 v13, v13
	v_sub_f32_e32 v37, v76, v11
	v_exp_f32_e32 v40, v37
	v_sub_f32_e32 v37, v77, v11
	v_add_f32_e32 v15, v13, v14
	v_sub_f32_e32 v14, v179, v11
	v_exp_f32_e32 v14, v14
	v_exp_f32_e32 v44, v37
	v_sub_f32_e32 v37, v78, v11
	v_exp_f32_e32 v48, v37
	v_add_f32_e32 v16, v14, v15
	v_sub_f32_e32 v15, v180, v11
	v_exp_f32_e32 v15, v15
	v_sub_f32_e32 v37, v79, v11
	v_exp_f32_e32 v56, v37
	v_sub_f32_e32 v37, v80, v11
	v_add_f32_e32 v17, v15, v16
	v_sub_f32_e32 v16, v70, v11
	v_exp_f32_e32 v16, v16
	v_exp_f32_e32 v60, v37
	v_sub_f32_e32 v41, v194, v11
	v_exp_f32_e32 v42, v41
	v_add_f32_e32 v18, v16, v17
	v_sub_f32_e32 v17, v71, v11
	v_exp_f32_e32 v17, v17
	v_sub_f32_e32 v41, v193, v11
	v_exp_f32_e32 v45, v41
	v_sub_f32_e32 v41, v192, v11
	v_add_f32_e32 v34, v17, v18
	v_sub_f32_e32 v18, v72, v11
	v_exp_f32_e32 v18, v18
	v_exp_f32_e32 v50, v41
	v_sub_f32_e32 v41, v191, v11
	v_exp_f32_e32 v54, v41
	v_add_f32_e32 v35, v18, v34
	v_sub_f32_e32 v34, v73, v11
	v_exp_f32_e32 v34, v34
	v_sub_f32_e32 v41, v189, v11
	v_exp_f32_e32 v64, v41
	v_sub_f32_e32 v41, v188, v11
	v_add_f32_e32 v36, v34, v35
	v_sub_f32_e32 v35, v74, v11
	v_exp_f32_e32 v35, v35
	v_exp_f32_e32 v72, v41
	v_sub_f32_e32 v46, v185, v11
	v_exp_f32_e32 v47, v46
	v_add_f32_e32 v36, v35, v36
	v_add_f32_e32 v36, v38, v36
	v_add_f32_e32 v36, v40, v36
	v_add_f32_e32 v36, v44, v36
	v_add_f32_e32 v36, v48, v36
	v_add_f32_e32 v36, v56, v36
	v_add_f32_e32 v37, v60, v36
	v_sub_f32_e32 v36, v196, v11
	v_exp_f32_e32 v36, v36
	v_sub_f32_e32 v46, v184, v11
	v_exp_f32_e32 v51, v46
	v_sub_f32_e32 v46, v183, v11
	v_add_f32_e32 v39, v36, v37
	v_sub_f32_e32 v37, v195, v11
	v_exp_f32_e32 v37, v37
	v_exp_f32_e32 v57, v46
	v_sub_f32_e32 v46, v182, v11
	v_exp_f32_e32 v62, v46
	v_add_f32_e32 v39, v37, v39
	v_add_f32_e32 v39, v42, v39
	v_add_f32_e32 v39, v45, v39
	v_add_f32_e32 v39, v50, v39
	v_add_f32_e32 v39, v54, v39
	v_add_f32_e32 v39, v64, v39
	v_add_f32_e32 v41, v72, v39
	v_sub_f32_e32 v39, v187, v11
	v_exp_f32_e32 v39, v39
	v_sub_f32_e32 v46, v181, v11
	v_exp_f32_e32 v76, v46
	v_sub_f32_e32 v46, v81, v11
	v_add_f32_e32 v43, v39, v41
	v_sub_f32_e32 v41, v186, v11
	v_exp_f32_e32 v41, v41
	v_exp_f32_e32 v80, v46
	v_sub_f32_e32 v52, v52, v11
	v_sub_f32_e32 v33, v33, v11
	v_add_f32_e32 v43, v41, v43
	v_add_f32_e32 v43, v47, v43
	v_add_f32_e32 v43, v51, v43
	v_add_f32_e32 v43, v57, v43
; #define MFMA32(a, b, c) __builtin_amdgcn_mfma_f32_32x32x16_bf16((a), (b), (c), 0, 0, 0)
; __device__ __forceinline__ void swa_item(int it, LAS unsigned char* lds, const bf16_t* SQ, const bf16_t* SK, const bf16_t* SV, const float* sinks, bf16_t* MIX, int tid, int wid, int lane) {
;     ...
;         float sum = 0.f;
; #pragma unroll
;         for (int t = 0; t < 5; ++t)
; #pragma unroll
;             for (int r = 0; r < 16; ++r) { const float p = __builtin_amdgcn_exp2f(st[t][r] - mx); st[t][r] = p; sum += p; }
;         sum += __shfl_xor(sum, 32); sum += __builtin_amdgcn_exp2f(sink2 - mx);
;         const float inv = 1.0f / sum;
;         f32x16 o0 = {}, o1 = {};
; #pragma unroll
;         for (int t = 0; t < 5; ++t)
; #pragma unroll
;             for (int s = 0; s < 2; ++s) {
;                 const bf16x8 pb = pack8(st[t], s);
;                 const int c0 = 32 * (qt + t) + 16 * s + 4 * hi;
;                 o0 = MFMA32(lds_cat_sw<VS>(VT, x, c0), pb, o0); o1 = MFMA32(lds_cat_sw<VS>(VT, 32 + x, c0), pb, o1);
;                 __builtin_amdgcn_sched_barrier(0);
;             }
	v_add_f32_e32 v43, v62, v43
	v_add_f32_e32 v43, v76, v43
	v_add_f32_e32 v46, v80, v43
	v_sub_f32_e32 v43, v203, v11
	v_exp_f32_e32 v43, v43
	v_exp_f32_e32 v182, v33
	v_sub_f32_e32 v31, v31, v11
	v_exp_f32_e32 v184, v31
	v_add_f32_e32 v49, v43, v46
	v_sub_f32_e32 v46, v53, v11
	v_exp_f32_e32 v46, v46
	v_exp_f32_e32 v53, v52
	v_sub_f32_e32 v52, v58, v11
	v_exp_f32_e32 v58, v52
	v_sub_f32_e32 v52, v65, v11
	v_exp_f32_e32 v65, v52
	v_sub_f32_e32 v52, v55, v11
	v_add_f32_e32 v49, v46, v49
	v_exp_f32_e32 v74, v52
	v_sub_f32_e32 v52, v202, v11
	v_add_f32_e32 v49, v53, v49
	v_exp_f32_e32 v177, v52
	v_sub_f32_e32 v52, v201, v11
	v_add_f32_e32 v49, v58, v49
	v_exp_f32_e32 v180, v52
	v_add_f32_e32 v49, v65, v49
	v_add_f32_e32 v49, v74, v49
	v_add_f32_e32 v49, v177, v49
	v_add_f32_e32 v52, v180, v49
	v_sub_f32_e32 v49, v200, v11
	v_exp_f32_e32 v49, v49
	v_sub_f32_e32 v32, v32, v11
	v_exp_f32_e32 v78, v32
	v_sub_f32_e32 v30, v30, v11
	v_add_f32_e32 v55, v49, v52
	v_sub_f32_e32 v52, v59, v11
	v_exp_f32_e32 v52, v52
	v_sub_f32_e32 v59, v61, v11
	v_exp_f32_e32 v61, v59
	v_sub_f32_e32 v59, v199, v11
	v_exp_f32_e32 v70, v59
	v_sub_f32_e32 v59, v198, v11
	v_exp_f32_e32 v77, v59
	v_sub_f32_e32 v59, v197, v11
	v_add_f32_e32 v55, v52, v55
	v_exp_f32_e32 v176, v59
	v_add_f32_e32 v55, v61, v55
	v_add_f32_e32 v55, v70, v55
	v_add_f32_e32 v55, v77, v55
	v_add_f32_e32 v55, v176, v55
	v_add_f32_e32 v33, v182, v55
	v_add_f32_e32 v31, v184, v33
	v_sub_f32_e32 v33, v205, v11
	v_exp_f32_e32 v55, v33
	v_sub_f32_e32 v33, v204, v11
	v_exp_f32_e32 v59, v33
	v_sub_f32_e32 v33, v63, v11
	v_exp_f32_e32 v73, v33
	v_add_f32_e32 v31, v55, v31
	v_exp_f32_e32 v178, v30
	v_sub_f32_e32 v29, v29, v11
	v_add_f32_e32 v31, v59, v31
	v_exp_f32_e32 v181, v29
	v_sub_f32_e32 v28, v28, v11
	v_add_f32_e32 v31, v73, v31
	v_exp_f32_e32 v186, v28
	v_sub_f32_e32 v27, v27, v11
	v_add_f32_e32 v31, v78, v31
	v_exp_f32_e32 v187, v27
	v_sub_f32_e32 v26, v26, v11
	v_add_f32_e32 v30, v178, v31
	v_exp_f32_e32 v63, v26
	v_sub_f32_e32 v25, v25, v11
	v_add_f32_e32 v29, v181, v30
	v_exp_f32_e32 v71, v25
	v_sub_f32_e32 v24, v24, v11
	v_add_f32_e32 v28, v186, v29
	v_exp_f32_e32 v81, v24
	v_sub_f32_e32 v23, v23, v11
	v_add_f32_e32 v27, v187, v28
	v_exp_f32_e32 v179, v23
	v_sub_f32_e32 v22, v22, v11
	v_add_f32_e32 v26, v63, v27
	v_exp_f32_e32 v183, v22
	v_sub_f32_e32 v21, v21, v11
	v_add_f32_e32 v25, v71, v26
	v_exp_f32_e32 v185, v21
	v_sub_f32_e32 v20, v20, v11
	v_add_f32_e32 v24, v81, v25
	v_exp_f32_e32 v189, v20
	v_sub_f32_e32 v19, v19, v11
	v_add_f32_e32 v23, v179, v24
	v_exp_f32_e32 v192, v19
	v_add_f32_e32 v22, v183, v23
	v_add_f32_e32 v21, v185, v22
	v_add_f32_e32 v20, v189, v21
	v_add_f32_e32 v19, v192, v20
	v_sub_f32_e32 v20, v175, v11
	v_exp_f32_e32 v75, v20
	v_sub_f32_e32 v20, v85, v11
	v_exp_f32_e32 v79, v20
	v_sub_f32_e32 v20, v84, v11
	v_exp_f32_e32 v84, v20
	v_sub_f32_e32 v20, v83, v11
	v_exp_f32_e32 v83, v20
	v_sub_f32_e32 v20, v69, v11
	v_add_f32_e32 v19, v75, v19
	v_exp_f32_e32 v85, v20
	v_sub_f32_e32 v20, v68, v11
	v_add_f32_e32 v19, v79, v19
	v_exp_f32_e32 v188, v20
	v_sub_f32_e32 v20, v67, v11
	v_add_f32_e32 v19, v84, v19
	v_exp_f32_e32 v194, v20
	v_sub_f32_e32 v20, v66, v11
	v_add_f32_e32 v19, v83, v19
	v_exp_f32_e32 v195, v20
	v_sub_f32_e32 v9, v9, v11
	v_add_f32_e32 v19, v85, v19
	v_exp_f32_e32 v67, v9
	v_sub_f32_e32 v8, v8, v11
	v_add_f32_e32 v19, v188, v19
	v_exp_f32_e32 v68, v8
	v_sub_f32_e32 v7, v7, v11
	v_add_f32_e32 v19, v194, v19
	v_exp_f32_e32 v69, v7
	v_sub_f32_e32 v6, v6, v11
	v_add_f32_e32 v19, v195, v19
	v_exp_f32_e32 v175, v6
	v_sub_f32_e32 v5, v5, v11
	v_add_f32_e32 v9, v67, v19
	v_exp_f32_e32 v191, v5
	v_sub_f32_e32 v4, v4, v11
	v_add_f32_e32 v8, v68, v9
	v_exp_f32_e32 v193, v4
	v_sub_f32_e32 v3, v3, v11
	v_add_f32_e32 v7, v69, v8
	v_exp_f32_e32 v196, v3
	v_sub_f32_e32 v2, v2, v11
	v_add_f32_e32 v6, v175, v7
	v_exp_f32_e32 v197, v2
	v_add_f32_e32 v5, v191, v6
	v_add_f32_e32 v4, v193, v5
	v_add_f32_e32 v3, v196, v4
	v_add_f32_e32 v2, v197, v3
	ds_bpermute_b32 v3, v174, v2
	v_cvt_pk_bf16_f32 v20, v10, v12
	v_cvt_pk_bf16_f32 v21, v13, v14
	v_cvt_pk_bf16_f32 v22, v15, v16
	v_cvt_pk_bf16_f32 v23, v17, v18
	s_waitcnt lgkmcnt(0)
	v_add_f32_e32 v2, v2, v3
	v_fma_f32 v3, v82, s14, -v11
	v_exp_f32_e32 v3, v3
	s_nop 0
	v_add_f32_e32 v66, v3, v2
	ds_read_b64 v[2:3], v135
	ds_read_b64 v[4:5], v136
	ds_read_b64 v[24:25], v137
	ds_read_b64 v[26:27], v138
	s_waitcnt lgkmcnt(2)
	v_mfma_f32_32x32x16_bf16 v[2:17], v[2:5], v[20:23], 0
	s_waitcnt lgkmcnt(0)
	v_mfma_f32_32x32x16_bf16 v[18:33], v[24:27], v[20:23], 0
	ds_read_b64 v[202:203], v139
	ds_read_b64 v[204:205], v140
	v_cvt_pk_bf16_f32 v198, v34, v35
	v_cvt_pk_bf16_f32 v199, v38, v40
	v_cvt_pk_bf16_f32 v200, v44, v48
	v_cvt_pk_bf16_f32 v201, v56, v60
	s_waitcnt lgkmcnt(0)
	s_nop 0
	v_mfma_f32_32x32x16_bf16 v[2:17], v[202:205], v[198:201], v[2:17]
	ds_read_b64 v[202:203], v141
	ds_read_b64 v[204:205], v142
	s_waitcnt lgkmcnt(0)
	v_mfma_f32_32x32x16_bf16 v[18:33], v[202:205], v[198:201], v[18:33]
	ds_read_b64 v[198:199], v135 offset:64
	ds_read_b64 v[200:201], v143
	v_cvt_pk_bf16_f32 v34, v36, v37
	v_cvt_pk_bf16_f32 v35, v42, v45
	v_cvt_pk_bf16_f32 v36, v50, v54
	v_cvt_pk_bf16_f32 v37, v64, v72
	s_waitcnt lgkmcnt(0)
	s_nop 0
	v_mfma_f32_32x32x16_bf16 v[2:17], v[198:201], v[34:37], v[2:17]
	ds_read_b64 v[198:199], v144
	ds_read_b64 v[200:201], v145
	s_waitcnt lgkmcnt(0)
	v_mfma_f32_32x32x16_bf16 v[18:33], v[198:201], v[34:37], v[18:33]
	v_cvt_pk_bf16_f32 v34, v39, v41
	ds_read_b64 v[38:39], v146
	ds_read_b64 v[40:41], v147
	v_cvt_pk_bf16_f32 v35, v47, v51
	v_cvt_pk_bf16_f32 v36, v57, v62
	v_cvt_pk_bf16_f32 v37, v76, v80
	s_waitcnt lgkmcnt(0)
; __device__ __forceinline__ unsigned cvtpk(float lo, float hi) { f32x2_t v = {lo, hi}; bf16x2_t b = __builtin_convertvector(v, bf16x2_t); return __builtin_bit_cast(unsigned, b); }
; #define MFMA32(a, b, c) __builtin_amdgcn_mfma_f32_32x32x16_bf16((a), (b), (c), 0, 0, 0)
; __device__ __forceinline__ void swa_item(int it, LAS unsigned char* lds, const bf16_t* SQ, const bf16_t* SK, const bf16_t* SV, const float* sinks, bf16_t* MIX, int tid, int wid, int lane) {
;     ...
;         for (int t = 0; t < 5; ++t)
; #pragma unroll
;             for (int s = 0; s < 2; ++s) {
;                 const bf16x8 pb = pack8(st[t], s);
;                 const int c0 = 32 * (qt + t) + 16 * s + 4 * hi;
;                 o0 = MFMA32(lds_cat_sw<VS>(VT, x, c0), pb, o0); o1 = MFMA32(lds_cat_sw<VS>(VT, 32 + x, c0), pb, o1);
;                 __builtin_amdgcn_sched_barrier(0);
;             }
;         bf16_t* op = MIX + qrow * 2048 + 1024 + head * 64 + 4 * hi;
; #pragma unroll
;         for (int g = 0; g < 4; ++g) {
;             u32x2 w0, w1; w0.x = cvtpk(o0[4 * g] * inv, o0[4 * g + 1] * inv); w0.y = cvtpk(o0[4 * g + 2] * inv, o0[4 * g + 3] * inv);
;             w1.x = cvtpk(o1[4 * g] * inv, o1[4 * g + 1] * inv); w1.y = cvtpk(o1[4 * g + 2] * inv, o1[4 * g + 3] * inv);
;             *(u32x2*)(op + 8 * g) = w0; *(u32x2*)(op + 32 + 8 * g) = w1;
;         }
	s_nop 0
	v_mfma_f32_32x32x16_bf16 v[2:17], v[38:41], v[34:37], v[2:17]
	ds_read_b64 v[38:39], v148
	ds_read_b64 v[40:41], v149
	s_waitcnt lgkmcnt(0)
	v_mfma_f32_32x32x16_bf16 v[18:33], v[38:41], v[34:37], v[18:33]
	ds_read_b64 v[38:39], v135 offset:128
	ds_read_b64 v[40:41], v152
	v_cvt_pk_bf16_f32 v34, v43, v46
	v_cvt_pk_bf16_f32 v35, v53, v58
	v_cvt_pk_bf16_f32 v36, v65, v74
	v_cvt_pk_bf16_f32 v37, v177, v180
	s_waitcnt lgkmcnt(0)
	s_nop 0
	v_mfma_f32_32x32x16_bf16 v[2:17], v[38:41], v[34:37], v[2:17]
	ds_read_b64 v[38:39], v153
	ds_read_b64 v[40:41], v154
	s_waitcnt lgkmcnt(0)
	v_mfma_f32_32x32x16_bf16 v[18:33], v[38:41], v[34:37], v[18:33]
	ds_read_b64 v[38:39], v155
	ds_read_b64 v[40:41], v156
	v_cvt_pk_bf16_f32 v34, v49, v52
	v_cvt_pk_bf16_f32 v35, v61, v70
	v_cvt_pk_bf16_f32 v36, v77, v176
	v_cvt_pk_bf16_f32 v37, v182, v184
	s_waitcnt lgkmcnt(0)
	s_nop 0
	v_mfma_f32_32x32x16_bf16 v[2:17], v[38:41], v[34:37], v[2:17]
	ds_read_b64 v[38:39], v157
	ds_read_b64 v[40:41], v158
	s_waitcnt lgkmcnt(0)
	v_mfma_f32_32x32x16_bf16 v[18:33], v[38:41], v[34:37], v[18:33]
	ds_read_b64 v[38:39], v135 offset:192
	ds_read_b64 v[40:41], v159
	v_cvt_pk_bf16_f32 v34, v55, v59
	v_cvt_pk_bf16_f32 v35, v73, v78
	v_cvt_pk_bf16_f32 v36, v178, v181
	v_cvt_pk_bf16_f32 v37, v186, v187
	s_waitcnt lgkmcnt(0)
	s_nop 0
	v_mfma_f32_32x32x16_bf16 v[2:17], v[38:41], v[34:37], v[2:17]
	ds_read_b64 v[38:39], v160
	ds_read_b64 v[40:41], v161
	s_waitcnt lgkmcnt(0)
	v_mfma_f32_32x32x16_bf16 v[18:33], v[38:41], v[34:37], v[18:33]
	ds_read_b64 v[38:39], v162
	ds_read_b64 v[40:41], v163
	v_cvt_pk_bf16_f32 v34, v63, v71
	v_cvt_pk_bf16_f32 v35, v81, v179
	v_cvt_pk_bf16_f32 v36, v183, v185
	v_cvt_pk_bf16_f32 v37, v189, v192
	s_waitcnt lgkmcnt(0)
	s_nop 0
	v_mfma_f32_32x32x16_bf16 v[2:17], v[38:41], v[34:37], v[2:17]
	ds_read_b64 v[38:39], v164
	ds_read_b64 v[40:41], v165
	s_waitcnt lgkmcnt(0)
	v_mfma_f32_32x32x16_bf16 v[18:33], v[38:41], v[34:37], v[18:33]
	ds_read_b64 v[38:39], v135 offset:256
	ds_read_b64 v[40:41], v166
	v_cvt_pk_bf16_f32 v34, v75, v79
	v_cvt_pk_bf16_f32 v35, v84, v83
	v_cvt_pk_bf16_f32 v36, v85, v188
	v_cvt_pk_bf16_f32 v37, v194, v195
	s_waitcnt lgkmcnt(0)
	s_nop 0
	v_mfma_f32_32x32x16_bf16 v[2:17], v[38:41], v[34:37], v[2:17]
	ds_read_b64 v[38:39], v167
	ds_read_b64 v[40:41], v168
	s_waitcnt lgkmcnt(0)
	v_mfma_f32_32x32x16_bf16 v[18:33], v[38:41], v[34:37], v[18:33]
	ds_read_b64 v[38:39], v169
	ds_read_b64 v[40:41], v170
	v_cvt_pk_bf16_f32 v34, v67, v68
	v_cvt_pk_bf16_f32 v35, v69, v175
	v_cvt_pk_bf16_f32 v36, v191, v193
	v_cvt_pk_bf16_f32 v37, v196, v197
	s_waitcnt lgkmcnt(0)
	s_nop 0
	v_mfma_f32_32x32x16_bf16 v[2:17], v[38:41], v[34:37], v[2:17]
	ds_read_b64 v[38:39], v171
	ds_read_b64 v[40:41], v172
	s_waitcnt lgkmcnt(0)
	v_mfma_f32_32x32x16_bf16 v[18:33], v[38:41], v[34:37], v[18:33]
	v_div_scale_f32 v34, s[40:41], v66, v66, 1.0
	v_rcp_f32_e32 v35, v34
	s_add_u32 s10, s10, 8
	s_addc_u32 s11, s11, 0
	v_lshl_add_u64 v[118:119], v[118:119], 0, s[30:31]
	v_fma_f32 v36, -v34, v35, 1.0
	v_fmac_f32_e32 v35, v36, v35
	v_div_scale_f32 v36, vcc, 1.0, v66, 1.0
	v_mul_f32_e32 v37, v36, v35
	v_fma_f32 v38, -v34, v37, v36
	v_fmac_f32_e32 v37, v38, v35
	v_fma_f32 v34, -v34, v37, v36
	v_div_fmas_f32 v34, v34, v35, v37
	v_div_fixup_f32 v34, v34, v66, 1.0
	v_pk_mul_f32 v[2:3], v[2:3], v[34:35] op_sel_hi:[1,0]
	v_pk_mul_f32 v[4:5], v[4:5], v[34:35] op_sel_hi:[1,0]
	v_cvt_pk_bf16_f32 v208, v2, v3
	v_cvt_pk_bf16_f32 v209, v4, v5
	v_pk_mul_f32 v[6:7], v[6:7], v[34:35] op_sel_hi:[1,0]
	v_pk_mul_f32 v[8:9], v[8:9], v[34:35] op_sel_hi:[1,0]
	v_cvt_pk_bf16_f32 v210, v6, v7
	v_cvt_pk_bf16_f32 v211, v8, v9
	v_pk_mul_f32 v[10:11], v[10:11], v[34:35] op_sel_hi:[1,0]
	v_pk_mul_f32 v[12:13], v[12:13], v[34:35] op_sel_hi:[1,0]
	v_cvt_pk_bf16_f32 v212, v10, v11
	v_cvt_pk_bf16_f32 v213, v12, v13
	v_pk_mul_f32 v[14:15], v[14:15], v[34:35] op_sel_hi:[1,0]
	v_pk_mul_f32 v[16:17], v[16:17], v[34:35] op_sel_hi:[1,0]
	v_cvt_pk_bf16_f32 v214, v14, v15
	v_cvt_pk_bf16_f32 v215, v16, v17
	v_pk_mul_f32 v[18:19], v[18:19], v[34:35] op_sel_hi:[1,0]
	v_pk_mul_f32 v[20:21], v[20:21], v[34:35] op_sel_hi:[1,0]
	v_cvt_pk_bf16_f32 v216, v18, v19
	v_cvt_pk_bf16_f32 v217, v20, v21
	v_pk_mul_f32 v[22:23], v[22:23], v[34:35] op_sel_hi:[1,0]
	v_pk_mul_f32 v[24:25], v[24:25], v[34:35] op_sel_hi:[1,0]
	v_cvt_pk_bf16_f32 v218, v22, v23
	v_cvt_pk_bf16_f32 v219, v24, v25
	v_pk_mul_f32 v[26:27], v[26:27], v[34:35] op_sel_hi:[1,0]
	v_pk_mul_f32 v[28:29], v[28:29], v[34:35] op_sel_hi:[1,0]
	v_cvt_pk_bf16_f32 v220, v26, v27
	v_cvt_pk_bf16_f32 v221, v28, v29
	v_pk_mul_f32 v[30:31], v[30:31], v[34:35] op_sel_hi:[1,0]
	v_pk_mul_f32 v[32:33], v[32:33], v[34:35] op_sel_hi:[1,0]
	v_cvt_pk_bf16_f32 v222, v30, v31
	v_cvt_pk_bf16_f32 v223, v32, v33
	v_add_co_u32_e32 v88, vcc, 8, v88
	v_and_b32_e32 v226, 32, v190
	v_mov_b32_e32 v227, 0
	v_lshrrev_b32_e32 v226, 2, v226
	v_lshl_add_u64 v[224:225], v[120:121], 0, v[226:227]
	v_permlane32_swap_b32_e32 v208, v210
	v_permlane32_swap_b32_e32 v209, v211
	global_store_dwordx4 v[224:225], v[208:211], off offset:-64
	v_permlane32_swap_b32_e32 v212, v214
	v_permlane32_swap_b32_e32 v213, v215
	global_store_dwordx4 v[224:225], v[212:215], off offset:-32
	v_permlane32_swap_b32_e32 v216, v218
	v_permlane32_swap_b32_e32 v217, v219
	global_store_dwordx4 v[224:225], v[216:219], off
	v_permlane32_swap_b32_e32 v220, v222
	v_permlane32_swap_b32_e32 v221, v223
	global_store_dwordx4 v[224:225], v[220:223], off offset:32
	v_lshl_add_u64 v[120:121], v[120:121], 0, s[30:31]
	s_and_b64 vcc, exec, vcc
	s_cbranch_vccnz .LBB0_1033
	v_readlane_b32 s64, v254, 36
	v_readlane_b32 s72, v254, 44
	v_readlane_b32 s73, v254, 45
	v_readlane_b32 s74, v254, 46
	v_readlane_b32 s75, v254, 47
	v_readlane_b32 s76, v254, 48
	v_readlane_b32 s77, v254, 49
	v_readlane_b32 s78, v254, 50
	v_readlane_b32 s79, v254, 51
	v_readlane_b32 s88, v255, 38
	v_readlane_b32 s68, v254, 40
	v_readlane_b32 s69, v254, 41
	v_readlane_b32 s70, v254, 42
	v_readlane_b32 s71, v254, 43
	s_mov_b64 s[82:83], s[78:79]
	s_mov_b64 s[96:97], s[52:53]
	v_readlane_b32 s52, v255, 42
	s_mov_b64 s[84:85], s[22:23]
	s_mov_b32 s86, s61
	v_readlane_b32 s89, v255, 39
	s_mov_b32 s87, s26
	s_mov_b64 s[80:81], s[76:77]
	s_mov_b64 s[78:79], s[74:75]
	s_mov_b64 s[76:77], s[72:73]
	s_mov_b64 s[74:75], s[70:71]
	s_mov_b64 s[72:73], s[68:69]
	s_mov_b64 s[94:95], s[36:37]
	s_mov_b64 s[36:37], s[18:19]
	v_readlane_b32 s53, v255, 43
	v_readlane_b32 s90, v255, 40
	v_readlane_b32 s91, v255, 41
	v_readlane_b32 s65, v254, 37
	v_readlane_b32 s66, v254, 38
	v_readlane_b32 s67, v254, 39
	s_branch .LBB0_1022
